# deeper software prefetch: V cache touches in front of the memory-attention softmax extended from 16 to 32 rows per wave, stacked on v82
# baseline (speedup 1.0000x reference)
; __device__ __forceinline__ void memattn_unit(const Ctx& C, int r0, const float* kp0, const float* vp0, unsigned char* lds, int lane) {
;     ...
;     __syncthreads();
; #pragma unroll
;     for (int rr = 0; rr < 4; ++rr) {
;         float* row = logits + (4 * w + rr) * 256; float x[4]; float mx = -INFINITY;
; #pragma unroll
;         for (int j = 0; j < 4; ++j) { x[j] = row[lane + 64 * j]; mx = fmaxf(mx, x[j]); }
;         mx = wave_max(mx); float s = 0.f;
; #pragma unroll
;         for (int j = 0; j < 4; ++j) { x[j] = __builtin_amdgcn_exp2f(x[j] - mx); s += x[j]; }
;         s = wave_sum(s); const float is = 1.0f / s;
; #pragma unroll
;         for (int j = 0; j < 4; ++j) row[lane + 64 * j] = x[j] * is;
;     }
;     ...
;         const float* vbase = vp0 + 128 * w + 2 * lane;
;         float2 va[16];
; #pragma unroll
;         for (int u = 0; u < 16; ++u) va[u] = *(const float2*)(vbase + (size_t)u * 1024);
.LBB0_3210:
	s_lshl_b32 s99, s34, 20
	s_lshr_b32 s98, s34, 12
	s_add_u32 s99, s42, s99
	s_addc_u32 s98, s43, s98
	v_lshlrev_b32_e32 v244, 3, v117
	v_mov_b32_e32 v245, 0
	v_mov_b32_e32 v246, s99
	v_mov_b32_e32 v247, s98
	v_lshl_add_u64 v[244:245], v[246:247], 0, v[244:245]
	global_load_dwordx2 v[228:229], v[244:245], off
	v_lshl_add_u64 v[244:245], v[244:245], 0, s[26:27]
	global_load_dwordx2 v[230:231], v[244:245], off
	v_lshl_add_u64 v[244:245], v[244:245], 0, s[26:27]
	global_load_dwordx2 v[232:233], v[244:245], off
	v_lshl_add_u64 v[244:245], v[244:245], 0, s[26:27]
	global_load_dwordx2 v[234:235], v[244:245], off
	v_lshl_add_u64 v[244:245], v[244:245], 0, s[26:27]
	global_load_dwordx2 v[236:237], v[244:245], off
	v_lshl_add_u64 v[244:245], v[244:245], 0, s[26:27]
	global_load_dwordx2 v[238:239], v[244:245], off
	v_lshl_add_u64 v[244:245], v[244:245], 0, s[26:27]
	global_load_dwordx2 v[240:241], v[244:245], off
	v_lshl_add_u64 v[244:245], v[244:245], 0, s[26:27]
	global_load_dwordx2 v[242:243], v[244:245], off
	v_lshl_add_u64 v[244:245], v[244:245], 0, s[26:27]
	global_load_dwordx2 v[228:229], v[244:245], off
	v_lshl_add_u64 v[244:245], v[244:245], 0, s[26:27]
	global_load_dwordx2 v[230:231], v[244:245], off
	v_lshl_add_u64 v[244:245], v[244:245], 0, s[26:27]
	global_load_dwordx2 v[232:233], v[244:245], off
	v_lshl_add_u64 v[244:245], v[244:245], 0, s[26:27]
	global_load_dwordx2 v[234:235], v[244:245], off
	v_lshl_add_u64 v[244:245], v[244:245], 0, s[26:27]
	global_load_dwordx2 v[236:237], v[244:245], off
	v_lshl_add_u64 v[244:245], v[244:245], 0, s[26:27]
	global_load_dwordx2 v[238:239], v[244:245], off
	v_lshl_add_u64 v[244:245], v[244:245], 0, s[26:27]
	global_load_dwordx2 v[240:241], v[244:245], off
	v_lshl_add_u64 v[244:245], v[244:245], 0, s[26:27]
	global_load_dwordx2 v[242:243], v[244:245], off
	v_lshl_add_u64 v[244:245], v[244:245], 0, s[26:27]
	global_load_dwordx2 v[228:229], v[244:245], off
	v_lshl_add_u64 v[244:245], v[244:245], 0, s[26:27]
	global_load_dwordx2 v[230:231], v[244:245], off
	v_lshl_add_u64 v[244:245], v[244:245], 0, s[26:27]
	global_load_dwordx2 v[232:233], v[244:245], off
	v_lshl_add_u64 v[244:245], v[244:245], 0, s[26:27]
	global_load_dwordx2 v[234:235], v[244:245], off
	v_lshl_add_u64 v[244:245], v[244:245], 0, s[26:27]
	global_load_dwordx2 v[236:237], v[244:245], off
	v_lshl_add_u64 v[244:245], v[244:245], 0, s[26:27]
	global_load_dwordx2 v[238:239], v[244:245], off
	v_lshl_add_u64 v[244:245], v[244:245], 0, s[26:27]
	global_load_dwordx2 v[240:241], v[244:245], off
	v_lshl_add_u64 v[244:245], v[244:245], 0, s[26:27]
	global_load_dwordx2 v[242:243], v[244:245], off
	v_lshl_add_u64 v[244:245], v[244:245], 0, s[26:27]
	global_load_dwordx2 v[228:229], v[244:245], off
	v_lshl_add_u64 v[244:245], v[244:245], 0, s[26:27]
	global_load_dwordx2 v[230:231], v[244:245], off
	v_lshl_add_u64 v[244:245], v[244:245], 0, s[26:27]
	global_load_dwordx2 v[232:233], v[244:245], off
	v_lshl_add_u64 v[244:245], v[244:245], 0, s[26:27]
	global_load_dwordx2 v[234:235], v[244:245], off
	v_lshl_add_u64 v[244:245], v[244:245], 0, s[26:27]
	global_load_dwordx2 v[236:237], v[244:245], off
	v_lshl_add_u64 v[244:245], v[244:245], 0, s[26:27]
	global_load_dwordx2 v[238:239], v[244:245], off
	v_lshl_add_u64 v[244:245], v[244:245], 0, s[26:27]
	global_load_dwordx2 v[240:241], v[244:245], off
	v_lshl_add_u64 v[244:245], v[244:245], 0, s[26:27]
	global_load_dwordx2 v[242:243], v[244:245], off
	v_and_b32_e32 v0, 64, v116
	v_add_u32_e32 v8, 64, v0
	v_xor_b32_e32 v0, 1, v116
	v_cmp_lt_i32_e32 vcc, v0, v8
	v_lshl_add_u32 v9, v117, 2, s33
	s_waitcnt lgkmcnt(0)
	s_barrier
	v_cndmask_b32_e32 v4, v116, v0, vcc
	ds_read2st64_b32 v[0:1], v9 offset1:1
	ds_read2st64_b32 v[2:3], v9 offset0:2 offset1:3
	v_lshlrev_b32_e32 v10, 2, v4
	v_xor_b32_e32 v13, 2, v116
	v_cmp_lt_i32_e32 vcc, v13, v8
	s_waitcnt lgkmcnt(1)
	v_max3_f32 v11, v0, s53, v1
	s_waitcnt lgkmcnt(0)
	v_max3_f32 v11, v11, v2, v3
	ds_bpermute_b32 v12, v10, v11
	v_cndmask_b32_e32 v13, v116, v13, vcc
	v_lshlrev_b32_e32 v13, 2, v13
	v_xor_b32_e32 v14, 4, v116
	v_cmp_lt_i32_e32 vcc, v14, v8
	s_waitcnt lgkmcnt(0)
	v_max_f32_e32 v12, v12, v12
	v_max_f32_e32 v11, v11, v12
	ds_bpermute_b32 v12, v13, v11
	v_cndmask_b32_e32 v14, v116, v14, vcc
	v_lshlrev_b32_e32 v14, 2, v14
	v_xor_b32_e32 v15, 8, v116
	v_cmp_lt_i32_e32 vcc, v15, v8
	s_waitcnt lgkmcnt(0)
	v_max_f32_e32 v12, v12, v12
	v_max_f32_e32 v11, v11, v12
	ds_bpermute_b32 v12, v14, v11
	v_cndmask_b32_e32 v15, v116, v15, vcc
	v_lshlrev_b32_e32 v15, 2, v15
	v_xor_b32_e32 v16, 16, v116
	v_cmp_lt_i32_e32 vcc, v16, v8
	s_waitcnt lgkmcnt(0)
	v_max_f32_e32 v12, v12, v12
	v_max_f32_e32 v11, v11, v12
	ds_bpermute_b32 v12, v15, v11
	v_cndmask_b32_e32 v16, v116, v16, vcc
	v_lshlrev_b32_e32 v16, 2, v16
	v_xor_b32_e32 v17, 32, v116
	v_cmp_lt_i32_e32 vcc, v17, v8
	s_waitcnt lgkmcnt(0)
	v_max_f32_e32 v12, v12, v12
	v_max_f32_e32 v11, v11, v12
	ds_bpermute_b32 v12, v16, v11
	v_cndmask_b32_e32 v8, v116, v17, vcc
	v_lshlrev_b32_e32 v8, 2, v8
	ds_read2st64_b32 v[4:5], v9 offset0:4 offset1:5
	ds_read2st64_b32 v[6:7], v9 offset0:6 offset1:7
	s_ashr_i32 s35, s34, 31
	s_waitcnt lgkmcnt(2)
	v_max_f32_e32 v12, v12, v12
	v_max_f32_e32 v11, v11, v12
	ds_bpermute_b32 v12, v8, v11
	v_mov_b32_e32 v34, 0
	s_mov_b32 s4, s44
	v_mov_b32_e32 v35, v34
	v_mov_b32_e32 v58, v34
	s_waitcnt lgkmcnt(0)
	v_max_f32_e32 v12, v12, v12
	v_max_f32_e32 v11, v11, v12
	v_sub_f32_e32 v0, v0, v11
	v_exp_f32_e32 v12, v0
	v_sub_f32_e32 v0, v1, v11
	v_exp_f32_e32 v17, v0
	v_sub_f32_e32 v0, v2, v11
	v_exp_f32_e32 v18, v0
	v_sub_f32_e32 v0, v3, v11
	v_exp_f32_e32 v11, v0
	v_add_f32_e32 v0, 0, v12
	v_add_f32_e32 v0, v17, v0
	v_add_f32_e32 v0, v18, v0
	v_add_f32_e32 v0, v11, v0
	ds_bpermute_b32 v1, v10, v0
	v_max3_f32 v2, v4, s53, v5
	v_max3_f32 v2, v2, v6, v7
	ds_bpermute_b32 v3, v10, v2
	v_mov_b32_e32 v59, v34
	s_waitcnt lgkmcnt(1)
; __device__ __forceinline__ void memattn_unit(const Ctx& C, int r0, const float* kp0, const float* vp0, unsigned char* lds, int lane) {
;     ...
; #pragma unroll
;     for (int rr = 0; rr < 4; ++rr) {
;         float* row = logits + (4 * w + rr) * 256; float x[4]; float mx = -INFINITY;
; #pragma unroll
;         for (int j = 0; j < 4; ++j) { x[j] = row[lane + 64 * j]; mx = fmaxf(mx, x[j]); }
;         mx = wave_max(mx); float s = 0.f;
; #pragma unroll
;         for (int j = 0; j < 4; ++j) { x[j] = __builtin_amdgcn_exp2f(x[j] - mx); s += x[j]; }
;         s = wave_sum(s); const float is = 1.0f / s;
; #pragma unroll
;         for (int j = 0; j < 4; ++j) row[lane + 64 * j] = x[j] * is;
;     }
	v_add_f32_e32 v0, v0, v1
	ds_bpermute_b32 v1, v13, v0
	v_mov_b32_e32 v68, v34
	s_waitcnt lgkmcnt(1)
	v_max_f32_e32 v3, v3, v3
	v_max_f32_e32 v2, v2, v3
	ds_bpermute_b32 v3, v13, v2
	s_waitcnt lgkmcnt(1)
	v_add_f32_e32 v0, v0, v1
	ds_bpermute_b32 v1, v14, v0
	v_mov_b32_e32 v69, v34
	v_mov_b32_e32 v72, v34
	s_waitcnt lgkmcnt(1)
	v_max_f32_e32 v3, v3, v3
	v_max_f32_e32 v2, v2, v3
	s_waitcnt lgkmcnt(0)
	v_add_f32_e32 v0, v0, v1
	ds_bpermute_b32 v1, v15, v0
	ds_bpermute_b32 v3, v14, v2
	v_mov_b32_e32 v73, v34
	v_mov_b32_e32 v56, v34
	v_mov_b32_e32 v57, v34
	s_waitcnt lgkmcnt(1)
	v_add_f32_e32 v0, v0, v1
	s_waitcnt lgkmcnt(0)
	v_max_f32_e32 v1, v3, v3
	v_max_f32_e32 v1, v2, v1
	ds_bpermute_b32 v2, v15, v1
	ds_bpermute_b32 v3, v16, v0
	v_mov_b32_e32 v64, v34
	v_mov_b32_e32 v65, v34
	v_mov_b32_e32 v70, v34
	s_waitcnt lgkmcnt(1)
	v_max_f32_e32 v2, v2, v2
	v_max_f32_e32 v1, v1, v2
	s_waitcnt lgkmcnt(0)
	v_add_f32_e32 v0, v0, v3
	ds_bpermute_b32 v2, v16, v1
	ds_bpermute_b32 v3, v8, v0
	v_mov_b32_e32 v71, v34
	v_mov_b32_e32 v74, v34
	v_mov_b32_e32 v75, v34
	s_waitcnt lgkmcnt(1)
	v_max_f32_e32 v2, v2, v2
	s_waitcnt lgkmcnt(0)
	v_add_f32_e32 v19, v0, v3
	v_max_f32_e32 v0, v1, v2
	ds_bpermute_b32 v1, v8, v0
	v_div_scale_f32 v20, s[0:1], v19, v19, 1.0
	v_rcp_f32_e32 v21, v20
	v_div_scale_f32 v26, vcc, 1.0, v19, 1.0
	s_waitcnt lgkmcnt(0)
	v_max_f32_e32 v1, v1, v1
	v_max_f32_e32 v0, v0, v1
	v_sub_f32_e32 v1, v4, v0
	v_exp_f32_e32 v22, v1
	v_sub_f32_e32 v1, v5, v0
	v_exp_f32_e32 v23, v1
	v_sub_f32_e32 v1, v6, v0
	v_exp_f32_e32 v24, v1
	v_sub_f32_e32 v0, v7, v0
	v_exp_f32_e32 v25, v0
	v_add_f32_e32 v0, 0, v22
	v_add_f32_e32 v0, v23, v0
	v_add_f32_e32 v0, v24, v0
	v_add_f32_e32 v0, v25, v0
	ds_bpermute_b32 v1, v10, v0
	v_fma_f32 v2, -v20, v21, 1.0
	v_fmac_f32_e32 v21, v2, v21
	v_mul_f32_e32 v27, v26, v21
	v_fma_f32 v28, -v20, v27, v26
	s_waitcnt lgkmcnt(0)
	v_add_f32_e32 v29, v0, v1
	ds_read2st64_b32 v[0:1], v9 offset0:8 offset1:9
	ds_read2st64_b32 v[2:3], v9 offset0:10 offset1:11
	ds_bpermute_b32 v30, v13, v29
	v_fmac_f32_e32 v27, v28, v21
	v_fma_f32 v20, -v20, v27, v26
	s_waitcnt lgkmcnt(2)
	v_max3_f32 v31, v0, s53, v1
	s_waitcnt lgkmcnt(1)
	v_max3_f32 v31, v31, v2, v3
	ds_bpermute_b32 v32, v10, v31
	s_waitcnt lgkmcnt(1)
	v_add_f32_e32 v26, v29, v30
	ds_bpermute_b32 v28, v14, v26
	v_div_fmas_f32 v20, v20, v21, v27
	v_div_fixup_f32 v19, v20, v19, 1.0
	s_waitcnt lgkmcnt(1)
	v_max_f32_e32 v29, v32, v32
	v_max_f32_e32 v29, v31, v29
	ds_bpermute_b32 v30, v13, v29
	s_waitcnt lgkmcnt(1)
	v_add_f32_e32 v21, v26, v28
	ds_bpermute_b32 v26, v15, v21
	v_mul_f32_e32 v12, v12, v19
	v_mul_f32_e32 v17, v17, v19
	s_waitcnt lgkmcnt(1)
	v_max_f32_e32 v27, v30, v30
	v_max_f32_e32 v27, v29, v27
	ds_bpermute_b32 v28, v14, v27
	s_waitcnt lgkmcnt(1)
	v_add_f32_e32 v20, v21, v26
	ds_read2st64_b32 v[4:5], v9 offset0:12 offset1:13
	ds_read2st64_b32 v[6:7], v9 offset0:14 offset1:15
	ds_write2st64_b32 v9, v12, v17 offset1:1
	v_mul_f32_e32 v18, v18, v19
	s_waitcnt lgkmcnt(3)
	v_max_f32_e32 v26, v28, v28
	v_max_f32_e32 v26, v27, v26
	ds_bpermute_b32 v27, v15, v26
	v_mul_f32_e32 v11, v11, v19
	ds_write2st64_b32 v9, v18, v11 offset0:2 offset1:3
	s_waitcnt lgkmcnt(4)
	v_max3_f32 v18, v4, s53, v5
	s_waitcnt lgkmcnt(3)
	v_max3_f32 v18, v18, v6, v7
	s_waitcnt lgkmcnt(1)
	v_max_f32_e32 v12, v27, v27
	v_max_f32_e32 v12, v26, v12
	ds_bpermute_b32 v17, v16, v12
	ds_bpermute_b32 v19, v10, v18
	ds_bpermute_b32 v21, v16, v20
	s_waitcnt lgkmcnt(2)
	v_max_f32_e32 v17, v17, v17
	v_max_f32_e32 v12, v12, v17
	ds_bpermute_b32 v17, v8, v12
	s_waitcnt lgkmcnt(1)
	v_add_f32_e32 v20, v20, v21
	ds_bpermute_b32 v21, v8, v20
	s_waitcnt lgkmcnt(1)
	v_max_f32_e32 v17, v17, v17
	v_max_f32_e32 v12, v12, v17
	v_sub_f32_e32 v0, v0, v12
	v_sub_f32_e32 v1, v1, v12
	v_sub_f32_e32 v2, v2, v12
	v_sub_f32_e32 v3, v3, v12
	v_max_f32_e32 v12, v19, v19
	v_max_f32_e32 v12, v18, v12
	ds_bpermute_b32 v18, v13, v12
	v_exp_f32_e32 v0, v0
	v_exp_f32_e32 v1, v1
	v_exp_f32_e32 v2, v2
	v_exp_f32_e32 v3, v3
	s_waitcnt lgkmcnt(0)
	v_max_f32_e32 v18, v18, v18
	v_max_f32_e32 v12, v12, v18
	ds_bpermute_b32 v18, v14, v12
	v_add_f32_e32 v17, 0, v0
	v_add_f32_e32 v17, v1, v17
	v_add_f32_e32 v17, v2, v17
	v_add_f32_e32 v17, v3, v17
	s_waitcnt lgkmcnt(0)
	v_max_f32_e32 v18, v18, v18
	v_max_f32_e32 v12, v12, v18
	ds_bpermute_b32 v18, v15, v12
	ds_bpermute_b32 v19, v10, v17
	v_add_f32_e32 v20, v20, v21
	v_div_scale_f32 v21, s[0:1], v20, v20, 1.0
	s_waitcnt lgkmcnt(1)
	v_max_f32_e32 v18, v18, v18
	v_max_f32_e32 v12, v12, v18
	ds_bpermute_b32 v18, v16, v12
	s_waitcnt lgkmcnt(1)
	v_add_f32_e32 v17, v17, v19
	ds_bpermute_b32 v19, v13, v17
	v_rcp_f32_e32 v26, v21
	s_waitcnt lgkmcnt(1)
	v_max_f32_e32 v18, v18, v18
	v_max_f32_e32 v12, v12, v18
	ds_bpermute_b32 v18, v8, v12
	s_waitcnt lgkmcnt(1)
; __device__ __forceinline__ void memattn_unit(const Ctx& C, int r0, const float* kp0, const float* vp0, unsigned char* lds, int lane) {
;     ...
; #pragma unroll
;     for (int rr = 0; rr < 4; ++rr) {
;         float* row = logits + (4 * w + rr) * 256; float x[4]; float mx = -INFINITY;
; #pragma unroll
;         for (int j = 0; j < 4; ++j) { x[j] = row[lane + 64 * j]; mx = fmaxf(mx, x[j]); }
;         mx = wave_max(mx); float s = 0.f;
; #pragma unroll
;         for (int j = 0; j < 4; ++j) { x[j] = __builtin_amdgcn_exp2f(x[j] - mx); s += x[j]; }
;         s = wave_sum(s); const float is = 1.0f / s;
; #pragma unroll
;         for (int j = 0; j < 4; ++j) row[lane + 64 * j] = x[j] * is;
;     }
;     __syncthreads();
;     {
;         const int hw = w >> 1;
;         float acc[8][2];
; #pragma unroll
;         for (int qi = 0; qi < 8; ++qi) { acc[qi][0] = 0.f; acc[qi][1] = 0.f; }
;         const float* vbase = vp0 + 128 * w + 2 * lane;
;         float2 va[16];
; #pragma unroll
;         for (int u = 0; u < 16; ++u) va[u] = *(const float2*)(vbase + (size_t)u * 1024);
	v_add_f32_e32 v17, v17, v19
	ds_bpermute_b32 v19, v14, v17
	v_fma_f32 v11, -v21, v26, 1.0
	v_fmac_f32_e32 v26, v11, v26
	s_waitcnt lgkmcnt(1)
	v_max_f32_e32 v18, v18, v18
	v_max_f32_e32 v12, v12, v18
	v_sub_f32_e32 v4, v4, v12
	v_exp_f32_e32 v4, v4
	v_sub_f32_e32 v5, v5, v12
	s_waitcnt lgkmcnt(0)
	v_add_f32_e32 v17, v17, v19
	v_exp_f32_e32 v5, v5
	v_sub_f32_e32 v6, v6, v12
	ds_bpermute_b32 v19, v15, v17
	v_exp_f32_e32 v6, v6
	v_sub_f32_e32 v7, v7, v12
	v_exp_f32_e32 v7, v7
	v_add_f32_e32 v12, 0, v4
	v_add_f32_e32 v12, v5, v12
	v_add_f32_e32 v12, v6, v12
	s_waitcnt lgkmcnt(0)
	v_add_f32_e32 v17, v17, v19
	v_add_f32_e32 v12, v7, v12
	ds_bpermute_b32 v19, v16, v17
	ds_bpermute_b32 v10, v10, v12
	v_div_scale_f32 v11, vcc, 1.0, v20, 1.0
	v_mul_f32_e32 v27, v11, v26
	s_waitcnt lgkmcnt(1)
	v_add_f32_e32 v17, v17, v19
	s_waitcnt lgkmcnt(0)
	v_add_f32_e32 v10, v12, v10
	ds_bpermute_b32 v18, v8, v17
	ds_bpermute_b32 v12, v13, v10
	v_fma_f32 v28, -v21, v27, v11
	v_fmac_f32_e32 v27, v28, v26
	v_fma_f32 v11, -v21, v27, v11
	s_waitcnt lgkmcnt(1)
	v_add_f32_e32 v13, v17, v18
	s_waitcnt lgkmcnt(0)
	v_add_f32_e32 v10, v10, v12
	v_div_scale_f32 v17, s[0:1], v13, v13, 1.0
	ds_bpermute_b32 v12, v14, v10
	v_rcp_f32_e32 v18, v17
	v_div_fmas_f32 v11, v11, v26, v27
	v_div_fixup_f32 v11, v11, v20, 1.0
	v_mul_f32_e32 v20, v22, v11
	v_mul_f32_e32 v21, v23, v11
	v_mul_f32_e32 v19, v24, v11
	v_mul_f32_e32 v11, v25, v11
	ds_write2st64_b32 v9, v19, v11 offset0:6 offset1:7
	v_fma_f32 v11, -v17, v18, 1.0
	s_waitcnt lgkmcnt(1)
	v_add_f32_e32 v10, v10, v12
	v_fmac_f32_e32 v18, v11, v18
	ds_bpermute_b32 v11, v15, v10
	v_div_scale_f32 v12, vcc, 1.0, v13, 1.0
	v_mul_f32_e32 v14, v12, v18
	v_fma_f32 v15, -v17, v14, v12
	s_waitcnt lgkmcnt(0)
	v_add_f32_e32 v10, v10, v11
	ds_bpermute_b32 v11, v16, v10
	v_fmac_f32_e32 v14, v15, v18
	v_fma_f32 v12, -v17, v14, v12
	v_div_fmas_f32 v12, v12, v18, v14
	ds_write2st64_b32 v9, v20, v21 offset0:4 offset1:5
	s_waitcnt lgkmcnt(1)
	v_add_f32_e32 v10, v10, v11
	ds_bpermute_b32 v8, v8, v10
	v_div_fixup_f32 v11, v12, v13, 1.0
	v_mul_f32_e32 v0, v0, v11
	v_mul_f32_e32 v1, v1, v11
	ds_write2st64_b32 v9, v0, v1 offset0:8 offset1:9
	s_waitcnt lgkmcnt(1)
	v_add_f32_e32 v0, v10, v8
	v_div_scale_f32 v1, s[0:1], v0, v0, 1.0
	v_rcp_f32_e32 v8, v1
	v_mul_f32_e32 v2, v2, v11
	v_mul_f32_e32 v3, v3, v11
	ds_write2st64_b32 v9, v2, v3 offset0:10 offset1:11
	v_fma_f32 v2, -v1, v8, 1.0
	v_fmac_f32_e32 v8, v2, v8
	v_div_scale_f32 v2, vcc, 1.0, v0, 1.0
	v_mul_f32_e32 v3, v2, v8
	v_fma_f32 v10, -v1, v3, v2
	v_fmac_f32_e32 v3, v10, v8
	v_fma_f32 v1, -v1, v3, v2
	v_div_fmas_f32 v1, v1, v8, v3
	v_div_fixup_f32 v0, v1, v0, 1.0
	v_mul_f32_e32 v1, v4, v0
	v_mul_f32_e32 v2, v5, v0
	ds_write2st64_b32 v9, v1, v2 offset0:12 offset1:13
	v_mul_f32_e32 v1, v6, v0
	v_mul_f32_e32 v0, v7, v0
	s_lshl_b64 s[0:1], s[34:35], 20
	ds_write2st64_b32 v9, v1, v0 offset0:14 offset1:15
	s_add_u32 s0, s42, s0
	v_lshlrev_b32_e32 v0, 1, v117
	s_addc_u32 s1, s43, s1
	v_ashrrev_i32_e32 v1, 31, v0
	v_lshl_add_u64 v[2:3], v[0:1], 2, s[0:1]
	v_add_co_u32_e32 v4, vcc, s51, v2
	s_waitcnt lgkmcnt(0)
	s_nop 0
	v_addc_co_u32_e32 v5, vcc, 0, v3, vcc
	v_add_co_u32_e32 v6, vcc, s21, v2
	s_barrier
	s_nop 0
	v_addc_co_u32_e32 v7, vcc, 0, v3, vcc
	global_load_dwordx2 v[54:55], v[4:5], off offset:-4096
	global_load_dwordx2 v[50:51], v[4:5], off
	global_load_dwordx2 v[48:49], v[6:7], off offset:-4096
	global_load_dwordx2 v[46:47], v[6:7], off
	v_add_co_u32_e32 v6, vcc, s54, v2
	s_mov_b32 s0, 0
	s_nop 0
	v_addc_co_u32_e32 v7, vcc, 0, v3, vcc
	v_add_co_u32_e32 v12, vcc, s55, v2
	s_nop 1
	v_addc_co_u32_e32 v13, vcc, 0, v3, vcc
	global_load_dwordx2 v[4:5], v[6:7], off offset:-4096
	global_load_dwordx2 v[10:11], v[6:7], off
	global_load_dwordx2 v[8:9], v[12:13], off offset:-4096
	s_nop 0
	global_load_dwordx2 v[6:7], v[12:13], off
	v_add_co_u32_e32 v12, vcc, s56, v2
	s_nop 1
	v_addc_co_u32_e32 v13, vcc, 0, v3, vcc
	v_add_co_u32_e32 v20, vcc, s57, v2
	s_nop 1
	v_addc_co_u32_e32 v21, vcc, 0, v3, vcc
	global_load_dwordx2 v[18:19], v[12:13], off offset:-4096
	global_load_dwordx2 v[16:17], v[12:13], off
	global_load_dwordx2 v[14:15], v[20:21], off offset:-4096
	s_nop 0
	global_load_dwordx2 v[12:13], v[20:21], off
	v_add_co_u32_e32 v20, vcc, 0xd000, v2
	s_nop 1
	v_addc_co_u32_e32 v21, vcc, 0, v3, vcc
	v_add_co_u32_e32 v22, vcc, 0xe000, v2
	s_nop 1
	v_addc_co_u32_e32 v23, vcc, 0, v3, vcc
	v_add_co_u32_e32 v26, vcc, 0xf000, v2
	s_nop 1
	v_addc_co_u32_e32 v27, vcc, 0, v3, vcc
	global_load_dwordx2 v[82:83], v[2:3], off
	global_load_dwordx2 v[24:25], v[20:21], off
	s_nop 0
	global_load_dwordx2 v[22:23], v[22:23], off
	s_nop 0
	global_load_dwordx2 v[20:21], v[26:27], off
